# S12 plus attention loops: cross-half row-max exchange via v_permlane32_swap instead of ds_bpermute (drops one LDS round trip and the lgkmcnt(0) drain per tile)
# speedup vs baseline: 1.0016x; 1.0016x over previous
.LBB0_612:
	s_sub_i32 s12, s58, 32
	s_lshl_b64 s[14:15], s[12:13], 11
	s_mov_b32 s59, s13
	v_lshl_add_u64 v[232:233], v[208:209], 0, s[14:15]
	s_lshl_b64 s[14:15], s[58:59], 11
	global_load_dwordx4 v[176:179], v[232:233], off
	v_lshl_add_u64 v[232:233], v[208:209], 0, s[14:15]
	s_lshl_b64 s[14:15], s[12:13], 7
	global_load_dwordx4 v[184:187], v[232:233], off
	v_lshl_add_u64 v[232:233], v[210:211], 0, s[14:15]
	global_load_dwordx4 v[188:191], v[232:233], off
	v_add_u32_e32 v0, s60, v215
	ds_read_b128 v[2:5], v0
	ds_read_b128 v[6:9], v0 offset:32
	v_mov_b64_e32 v[126:127], v[94:95]
	v_mov_b64_e32 v[124:125], v[92:93]
	v_mov_b64_e32 v[122:123], v[90:91]
	s_waitcnt lgkmcnt(1)
	v_mfma_f32_32x32x16_bf16 v[96:111], v[2:5], v[128:131], v[80:95]
	ds_read_b128 v[2:5], v0 offset:12800
	ds_read_b128 v[10:13], v0 offset:12832
	v_mov_b64_e32 v[120:121], v[88:89]
	v_mov_b64_e32 v[118:119], v[86:87]
	v_mov_b64_e32 v[116:117], v[84:85]
	v_mov_b64_e32 v[114:115], v[82:83]
	v_mov_b64_e32 v[112:113], v[80:81]
	s_waitcnt lgkmcnt(2)
	v_mfma_f32_32x32x16_bf16 v[96:111], v[6:9], v[132:135], v[96:111]
	s_mov_b32 s71, s9
	s_mov_b32 s72, s8
	s_waitcnt lgkmcnt(1)
	v_mfma_f32_32x32x16_bf16 v[112:127], v[2:5], v[128:131], v[112:127]
	ds_read_b128 v[2:5], v0 offset:64
	ds_read_b128 v[6:9], v0 offset:96
	s_waitcnt lgkmcnt(2)
	v_mfma_f32_32x32x16_bf16 v[112:127], v[10:13], v[132:135], v[112:127]
	s_waitcnt lgkmcnt(1)
	v_mfma_f32_32x32x16_bf16 v[96:111], v[2:5], v[136:139], v[96:111]
	ds_read_b128 v[2:5], v0 offset:12864
	ds_read_b128 v[10:13], v0 offset:12896
	s_waitcnt lgkmcnt(1)
	v_mfma_f32_32x32x16_bf16 v[112:127], v[2:5], v[136:139], v[112:127]
	v_mfma_f32_32x32x16_bf16 v[96:111], v[6:9], v[140:143], v[96:111]
	ds_read_b128 v[2:5], v0 offset:128
	ds_read_b128 v[6:9], v0 offset:160
	s_waitcnt lgkmcnt(2)
	v_mfma_f32_32x32x16_bf16 v[112:127], v[10:13], v[140:143], v[112:127]
	s_waitcnt lgkmcnt(1)
	v_mfma_f32_32x32x16_bf16 v[96:111], v[2:5], v[144:147], v[96:111]
	ds_read_b128 v[2:5], v0 offset:12928
	ds_read_b128 v[10:13], v0 offset:12960
	s_waitcnt lgkmcnt(1)
	v_mfma_f32_32x32x16_bf16 v[112:127], v[2:5], v[144:147], v[112:127]
	v_mfma_f32_32x32x16_bf16 v[96:111], v[6:9], v[148:151], v[96:111]
	ds_read_b128 v[2:5], v0 offset:192
	ds_read_b128 v[6:9], v0 offset:224
	s_waitcnt lgkmcnt(2)
	v_mfma_f32_32x32x16_bf16 v[112:127], v[10:13], v[148:151], v[112:127]
	s_waitcnt lgkmcnt(1)
	v_mfma_f32_32x32x16_bf16 v[96:111], v[2:5], v[152:155], v[96:111]
	ds_read_b128 v[2:5], v0 offset:12992
	ds_read_b128 v[10:13], v0 offset:13024
	s_waitcnt lgkmcnt(1)
	v_mfma_f32_32x32x16_bf16 v[112:127], v[2:5], v[152:155], v[112:127]
	v_mfma_f32_32x32x16_bf16 v[96:111], v[6:9], v[156:159], v[96:111]
	ds_read_b128 v[2:5], v0 offset:256
	ds_read_b128 v[6:9], v0 offset:288
	s_waitcnt lgkmcnt(2)
	v_mfma_f32_32x32x16_bf16 v[112:127], v[10:13], v[156:159], v[112:127]
	s_waitcnt lgkmcnt(1)
	v_mfma_f32_32x32x16_bf16 v[96:111], v[2:5], v[160:163], v[96:111]
	ds_read_b128 v[2:5], v0 offset:13056
	ds_read_b128 v[10:13], v0 offset:13088
	s_waitcnt lgkmcnt(1)
	v_mfma_f32_32x32x16_bf16 v[112:127], v[2:5], v[160:163], v[112:127]
	ds_read_b128 v[2:5], v0 offset:320
	v_mfma_f32_32x32x16_bf16 v[96:111], v[6:9], v[164:167], v[96:111]
	s_waitcnt lgkmcnt(1)
	v_mfma_f32_32x32x16_bf16 v[112:127], v[10:13], v[164:167], v[112:127]
	ds_read_b128 v[6:9], v0 offset:13120
	ds_read_b128 v[10:13], v0 offset:352
	s_waitcnt lgkmcnt(2)
	v_mfma_f32_32x32x16_bf16 v[96:111], v[2:5], v[168:171], v[96:111]
	s_add_i32 s12, s58, 0xffffffa0
	ds_read_b128 v[230:233], v0 offset:13152
	s_waitcnt lgkmcnt(2)
	v_mfma_f32_32x32x16_bf16 v[112:127], v[6:9], v[168:171], v[112:127]
	s_lshl_b64 s[14:15], s[12:13], 1
	v_lshl_add_u64 v[8:9], v[218:219], 0, s[14:15]
	v_lshl_add_u64 v[2:3], v[206:207], 0, s[14:15]
	global_load_dwordx4 v[2:5], v[2:3], off
	s_nop 0
	s_nop 0
	global_load_dwordx4 v[6:9], v[8:9], off
	s_waitcnt lgkmcnt(1)
	v_mfma_f32_32x32x16_bf16 v[96:111], v[10:13], v[172:175], v[96:111]
	s_waitcnt lgkmcnt(0)
	v_mfma_f32_32x32x16_bf16 v[112:127], v[230:233], v[172:175], v[112:127]
	s_add_i32 s8, s9, 0
	s_add_i32 s8, s8, 0x12c00
	v_add_u32_e32 v0, s8, v227
	v_add_u32_e32 v231, v0, v226
	v_add_u32_e32 v229, 0x1000, v231
	v_add_u32_e32 v230, 0x2000, v231
	v_add_u32_e32 v252, 0x3000, v231
	ds_read2_b64 v[234:237], v231 offset1:2
	ds_read2_b64 v[238:241], v229 offset0:32 offset1:34
	ds_read2_b64 v[244:247], v230 offset0:64 offset1:66
	ds_read2_b64 v[248:251], v252 offset0:96 offset1:98
	s_nop 2
	v_max_f32_e32 v0, v96, v96
	v_max_f32_e32 v0, 0xff800000, v0
	v_max3_f32 v0, v0, v97, v98
	s_waitcnt lgkmcnt(3)
	v_mfma_f32_32x32x16_bf16 v[64:79], v[234:237], v[200:203], v[64:79]
	ds_read2_b64 v[234:237], v231 offset0:4 offset1:6
	v_max3_f32 v10, v112, s64, v113
	v_max3_f32 v14, v10, v114, v115
	s_waitcnt lgkmcnt(3)
	v_mfma_f32_32x32x16_bf16 v[48:63], v[238:241], v[200:203], v[48:63]
	ds_read2_b64 v[238:241], v229 offset0:36 offset1:38
	v_max3_f32 v0, v0, v99, v100
	v_max3_f32 v14, v14, v116, v117
	v_max3_f32 v0, v0, v101, v102
	v_max3_f32 v14, v14, v118, v119
	s_waitcnt lgkmcnt(3)
	v_mfma_f32_32x32x16_bf16 v[32:47], v[244:247], v[200:203], v[32:47]
	ds_read2_b64 v[244:247], v230 offset0:68 offset1:70
	v_max3_f32 v0, v0, v103, v104
	v_max3_f32 v14, v14, v120, v121
	v_max3_f32 v0, v0, v105, v106
	v_max3_f32 v14, v14, v122, v123
	s_waitcnt lgkmcnt(3)
	v_mfma_f32_32x32x16_bf16 v[16:31], v[248:251], v[200:203], v[16:31]
	ds_read2_b64 v[248:251], v252 offset0:100 offset1:102
	v_max3_f32 v0, v0, v107, v108
	v_max3_f32 v10, v14, v124, v125
	v_max3_f32 v0, v0, v109, v110
	v_max3_f32 v14, v10, v126, v127
	v_max3_f32 v0, v0, v111, v14
	v_mov_b32_e32 v14, v0
	s_waitcnt lgkmcnt(3)
	v_mfma_f32_32x32x16_bf16 v[64:79], v[234:237], v[196:199], v[64:79]
	ds_read2_b64 v[234:237], v231 offset0:8 offset1:10
	v_permlane32_swap_b32_e32 v14, v0
	v_max_f32_e32 v14, v14, v14
	v_max_f32_e32 v0, v0, v14
	v_cmp_lt_f32_e32 vcc, s65, v0
	s_cbranch_vccz .LBB0_614
	v_max_f32_e32 v0, v0, v0
	v_max_f32_e32 v0, 0, v0
	v_add_f32_e32 v217, v217, v0
	v_pk_add_f32 v[96:97], v[96:97], v[0:1] op_sel_hi:[1,0] neg_lo:[0,1] neg_hi:[0,1]
	v_pk_add_f32 v[112:113], v[112:113], v[0:1] op_sel_hi:[1,0] neg_lo:[0,1] neg_hi:[0,1]
	v_pk_add_f32 v[98:99], v[98:99], v[0:1] op_sel_hi:[1,0] neg_lo:[0,1] neg_hi:[0,1]
	v_pk_add_f32 v[114:115], v[114:115], v[0:1] op_sel_hi:[1,0] neg_lo:[0,1] neg_hi:[0,1]
	v_pk_add_f32 v[100:101], v[100:101], v[0:1] op_sel_hi:[1,0] neg_lo:[0,1] neg_hi:[0,1]
	v_pk_add_f32 v[116:117], v[116:117], v[0:1] op_sel_hi:[1,0] neg_lo:[0,1] neg_hi:[0,1]
	v_pk_add_f32 v[102:103], v[102:103], v[0:1] op_sel_hi:[1,0] neg_lo:[0,1] neg_hi:[0,1]
	v_pk_add_f32 v[118:119], v[118:119], v[0:1] op_sel_hi:[1,0] neg_lo:[0,1] neg_hi:[0,1]
	v_pk_add_f32 v[104:105], v[104:105], v[0:1] op_sel_hi:[1,0] neg_lo:[0,1] neg_hi:[0,1]
	v_pk_add_f32 v[120:121], v[120:121], v[0:1] op_sel_hi:[1,0] neg_lo:[0,1] neg_hi:[0,1]
	v_pk_add_f32 v[106:107], v[106:107], v[0:1] op_sel_hi:[1,0] neg_lo:[0,1] neg_hi:[0,1]
	v_pk_add_f32 v[122:123], v[122:123], v[0:1] op_sel_hi:[1,0] neg_lo:[0,1] neg_hi:[0,1]
	v_pk_add_f32 v[108:109], v[108:109], v[0:1] op_sel_hi:[1,0] neg_lo:[0,1] neg_hi:[0,1]
	v_pk_add_f32 v[124:125], v[124:125], v[0:1] op_sel_hi:[1,0] neg_lo:[0,1] neg_hi:[0,1]
	v_pk_add_f32 v[110:111], v[110:111], v[0:1] op_sel_hi:[1,0] neg_lo:[0,1] neg_hi:[0,1]
	v_pk_add_f32 v[126:127], v[126:127], v[0:1] op_sel_hi:[1,0] neg_lo:[0,1] neg_hi:[0,1]
	v_exp_f32_e64 v0, -v0
	v_xor_b32_e32 v80, 0x80000000, v217
	v_mov_b32_e32 v81, v80
	v_mov_b32_e32 v82, v80
	v_mov_b32_e32 v83, v80
	v_mov_b32_e32 v84, v80
	v_mov_b32_e32 v85, v80
	v_mov_b32_e32 v86, v80
	v_mov_b32_e32 v87, v80
	v_mov_b32_e32 v88, v80
	v_mov_b32_e32 v89, v80
	v_mov_b32_e32 v90, v80
	v_mov_b32_e32 v91, v80
	v_mov_b32_e32 v92, v80
	v_mov_b32_e32 v93, v80
	v_mov_b32_e32 v94, v80
	v_mov_b32_e32 v95, v80
	s_branch .LBB0_615

.LBB0_615:
	s_waitcnt lgkmcnt(3)
	v_mfma_f32_32x32x16_bf16 v[48:63], v[238:241], v[196:199], v[48:63]
	ds_read2_b64 v[238:241], v229 offset0:40 offset1:42
	v_add_u32_e32 v232, s70, v212
	v_add_u32_e32 v233, s70, v214
	s_waitcnt vmcnt(4)
	ds_write_b128 v232, v[176:179]
	v_exp_f32_e32 v220, v96
	v_exp_f32_e32 v221, v112
	v_exp_f32_e32 v14, v97
	v_exp_f32_e32 v15, v113
	s_waitcnt lgkmcnt(4)
	v_mfma_f32_32x32x16_bf16 v[32:47], v[244:247], v[196:199], v[32:47]
	ds_read2_b64 v[244:247], v230 offset0:72 offset1:74
	s_waitcnt vmcnt(3)
	ds_write_b128 v232, v[184:187] offset:12800
	v_exp_f32_e32 v12, v98
	v_exp_f32_e32 v13, v114
	v_exp_f32_e32 v10, v99
	v_exp_f32_e32 v11, v115
	s_waitcnt lgkmcnt(5)
	v_mfma_f32_32x32x16_bf16 v[16:31], v[248:251], v[196:199], v[16:31]
	ds_read2_b64 v[248:251], v252 offset0:104 offset1:106
	s_waitcnt vmcnt(2)
	ds_write_b128 v233, v[188:191] offset:256
	v_exp_f32_e32 v98, v100
	v_exp_f32_e32 v99, v116
	v_exp_f32_e32 v96, v101
	v_exp_f32_e32 v97, v117
	s_waitcnt lgkmcnt(6)
	v_mfma_f32_32x32x16_bf16 v[64:79], v[234:237], v[192:195], v[64:79]
	ds_read2_b64 v[234:237], v231 offset0:12 offset1:14
	v_exp_f32_e32 v112, v102
	v_exp_f32_e32 v113, v118
	v_exp_f32_e32 v100, v103
	v_exp_f32_e32 v101, v119
	s_waitcnt lgkmcnt(6)
	v_mfma_f32_32x32x16_bf16 v[48:63], v[238:241], v[192:195], v[48:63]
	ds_read2_b64 v[238:241], v229 offset0:44 offset1:46
	v_exp_f32_e32 v114, v104
	v_exp_f32_e32 v115, v120
	v_exp_f32_e32 v102, v105
	v_exp_f32_e32 v103, v121
	s_waitcnt lgkmcnt(5)
	v_mfma_f32_32x32x16_bf16 v[32:47], v[244:247], v[192:195], v[32:47]
	ds_read2_b64 v[244:247], v230 offset0:76 offset1:78
	v_exp_f32_e32 v116, v106
	v_exp_f32_e32 v117, v122
	v_exp_f32_e32 v104, v107
	v_exp_f32_e32 v105, v123
	s_waitcnt lgkmcnt(4)
	v_mfma_f32_32x32x16_bf16 v[16:31], v[248:251], v[192:195], v[16:31]
	ds_read2_b64 v[248:251], v252 offset0:108 offset1:110
	v_exp_f32_e32 v118, v108
	v_exp_f32_e32 v119, v124
	v_exp_f32_e32 v106, v109
	v_exp_f32_e32 v107, v125
	s_waitcnt lgkmcnt(3)
	v_mfma_f32_32x32x16_bf16 v[64:79], v[234:237], v[180:183], v[64:79]
	v_exp_f32_e32 v120, v110
	v_exp_f32_e32 v121, v126
	v_exp_f32_e32 v108, v111
	v_exp_f32_e32 v109, v127
	s_waitcnt lgkmcnt(2)
	v_mfma_f32_32x32x16_bf16 v[48:63], v[238:241], v[180:183], v[48:63]
	v_cvt_pk_bf16_f32 v200, v220, v14
	v_cvt_pk_bf16_f32 v201, v12, v10
	v_cvt_pk_bf16_f32 v202, v98, v96
	v_cvt_pk_bf16_f32 v203, v112, v100
	v_cvt_pk_bf16_f32 v196, v114, v102
	v_cvt_pk_bf16_f32 v197, v116, v104
	v_cvt_pk_bf16_f32 v198, v118, v106
	v_cvt_pk_bf16_f32 v199, v120, v108
	s_waitcnt lgkmcnt(1)
	v_mfma_f32_32x32x16_bf16 v[32:47], v[244:247], v[180:183], v[32:47]
	v_cvt_pk_bf16_f32 v192, v221, v15
	v_cvt_pk_bf16_f32 v193, v13, v11
	v_cvt_pk_bf16_f32 v194, v99, v97
	v_cvt_pk_bf16_f32 v195, v113, v101
	s_waitcnt lgkmcnt(0)
	v_mfma_f32_32x32x16_bf16 v[16:31], v[248:251], v[180:183], v[16:31]
	v_cvt_pk_bf16_f32 v180, v115, v103
	v_cvt_pk_bf16_f32 v181, v117, v105
	v_cvt_pk_bf16_f32 v182, v119, v107
	v_cvt_pk_bf16_f32 v183, v121, v109
	v_cmp_gt_f32_e32 vcc, 1.0, v0
	s_cbranch_vccz .LBB0_617
	v_pk_mul_f32 v[78:79], v[0:1], v[78:79] op_sel_hi:[0,1]
	v_pk_mul_f32 v[76:77], v[0:1], v[76:77] op_sel_hi:[0,1]
	v_pk_mul_f32 v[74:75], v[0:1], v[74:75] op_sel_hi:[0,1]
	v_pk_mul_f32 v[72:73], v[0:1], v[72:73] op_sel_hi:[0,1]
	v_pk_mul_f32 v[70:71], v[0:1], v[70:71] op_sel_hi:[0,1]
	v_pk_mul_f32 v[68:69], v[0:1], v[68:69] op_sel_hi:[0,1]
	v_pk_mul_f32 v[66:67], v[0:1], v[66:67] op_sel_hi:[0,1]
	v_pk_mul_f32 v[64:65], v[0:1], v[64:65] op_sel_hi:[0,1]
	v_pk_mul_f32 v[62:63], v[0:1], v[62:63] op_sel_hi:[0,1]
	v_pk_mul_f32 v[60:61], v[0:1], v[60:61] op_sel_hi:[0,1]
	v_pk_mul_f32 v[58:59], v[0:1], v[58:59] op_sel_hi:[0,1]
	v_pk_mul_f32 v[56:57], v[0:1], v[56:57] op_sel_hi:[0,1]
	v_pk_mul_f32 v[54:55], v[0:1], v[54:55] op_sel_hi:[0,1]
	v_pk_mul_f32 v[52:53], v[0:1], v[52:53] op_sel_hi:[0,1]
	v_pk_mul_f32 v[50:51], v[0:1], v[50:51] op_sel_hi:[0,1]
	v_pk_mul_f32 v[48:49], v[0:1], v[48:49] op_sel_hi:[0,1]
	v_pk_mul_f32 v[46:47], v[0:1], v[46:47] op_sel_hi:[0,1]
	v_pk_mul_f32 v[44:45], v[0:1], v[44:45] op_sel_hi:[0,1]
	v_pk_mul_f32 v[42:43], v[0:1], v[42:43] op_sel_hi:[0,1]
	v_pk_mul_f32 v[40:41], v[0:1], v[40:41] op_sel_hi:[0,1]
	v_pk_mul_f32 v[38:39], v[0:1], v[38:39] op_sel_hi:[0,1]
	v_pk_mul_f32 v[36:37], v[0:1], v[36:37] op_sel_hi:[0,1]
	v_pk_mul_f32 v[34:35], v[0:1], v[34:35] op_sel_hi:[0,1]
	v_pk_mul_f32 v[32:33], v[0:1], v[32:33] op_sel_hi:[0,1]
	v_pk_mul_f32 v[30:31], v[0:1], v[30:31] op_sel_hi:[0,1]
	v_pk_mul_f32 v[28:29], v[0:1], v[28:29] op_sel_hi:[0,1]
	v_pk_mul_f32 v[26:27], v[0:1], v[26:27] op_sel_hi:[0,1]
	v_pk_mul_f32 v[24:25], v[0:1], v[24:25] op_sel_hi:[0,1]
	v_pk_mul_f32 v[22:23], v[0:1], v[22:23] op_sel_hi:[0,1]
	v_pk_mul_f32 v[20:21], v[0:1], v[20:21] op_sel_hi:[0,1]
	v_pk_mul_f32 v[18:19], v[0:1], v[18:19] op_sel_hi:[0,1]
	v_pk_mul_f32 v[16:17], v[0:1], v[16:17] op_sel_hi:[0,1]

.LBB0_624:
	v_add_u32_e32 v0, s70, v215
	ds_read_b128 v[2:5], v0
	ds_read_b128 v[6:9], v0 offset:32
	v_mov_b64_e32 v[110:111], v[94:95]
	v_mov_b64_e32 v[108:109], v[92:93]
	v_mov_b64_e32 v[106:107], v[90:91]
	s_waitcnt lgkmcnt(1)
	v_mfma_f32_32x32x16_bf16 v[112:127], v[2:5], v[128:131], v[80:95]
	ds_read_b128 v[2:5], v0 offset:12800
	ds_read_b128 v[10:13], v0 offset:12832
	v_mov_b64_e32 v[104:105], v[88:89]
	v_mov_b64_e32 v[102:103], v[86:87]
	v_mov_b64_e32 v[100:101], v[84:85]
	v_mov_b64_e32 v[98:99], v[82:83]
	v_mov_b64_e32 v[96:97], v[80:81]
	s_waitcnt lgkmcnt(2)
	v_mfma_f32_32x32x16_bf16 v[112:127], v[6:9], v[132:135], v[112:127]
	s_add_i32 s12, s58, 0xffffffa0
	s_lshl_b64 s[8:9], s[12:13], 1
	s_waitcnt lgkmcnt(1)
	v_mfma_f32_32x32x16_bf16 v[96:111], v[2:5], v[128:131], v[96:111]
	ds_read_b128 v[2:5], v0 offset:64
	ds_read_b128 v[6:9], v0 offset:96
	s_waitcnt lgkmcnt(2)
	v_mfma_f32_32x32x16_bf16 v[96:111], v[10:13], v[132:135], v[96:111]
	s_waitcnt lgkmcnt(1)
	v_mfma_f32_32x32x16_bf16 v[112:127], v[2:5], v[136:139], v[112:127]
	ds_read_b128 v[2:5], v0 offset:12864
	ds_read_b128 v[10:13], v0 offset:12896
	s_waitcnt lgkmcnt(1)
	v_mfma_f32_32x32x16_bf16 v[96:111], v[2:5], v[136:139], v[96:111]
	v_mfma_f32_32x32x16_bf16 v[112:127], v[6:9], v[140:143], v[112:127]
	ds_read_b128 v[2:5], v0 offset:128
	ds_read_b128 v[6:9], v0 offset:160
	s_waitcnt lgkmcnt(2)
	v_mfma_f32_32x32x16_bf16 v[96:111], v[10:13], v[140:143], v[96:111]
	s_waitcnt lgkmcnt(1)
	v_mfma_f32_32x32x16_bf16 v[112:127], v[2:5], v[144:147], v[112:127]
	ds_read_b128 v[2:5], v0 offset:12928
	ds_read_b128 v[10:13], v0 offset:12960
	s_waitcnt lgkmcnt(1)
	v_mfma_f32_32x32x16_bf16 v[96:111], v[2:5], v[144:147], v[96:111]
	v_mfma_f32_32x32x16_bf16 v[112:127], v[6:9], v[148:151], v[112:127]
	ds_read_b128 v[2:5], v0 offset:192
	ds_read_b128 v[6:9], v0 offset:224
	s_waitcnt lgkmcnt(2)
	v_mfma_f32_32x32x16_bf16 v[96:111], v[10:13], v[148:151], v[96:111]
	s_waitcnt lgkmcnt(1)
	v_mfma_f32_32x32x16_bf16 v[112:127], v[2:5], v[152:155], v[112:127]
	ds_read_b128 v[2:5], v0 offset:12992
	ds_read_b128 v[10:13], v0 offset:13024
	s_waitcnt lgkmcnt(1)
	v_mfma_f32_32x32x16_bf16 v[96:111], v[2:5], v[152:155], v[96:111]
	v_mfma_f32_32x32x16_bf16 v[112:127], v[6:9], v[156:159], v[112:127]
	ds_read_b128 v[2:5], v0 offset:256
	ds_read_b128 v[6:9], v0 offset:288
	s_waitcnt lgkmcnt(2)
	v_mfma_f32_32x32x16_bf16 v[96:111], v[10:13], v[156:159], v[96:111]
	s_waitcnt lgkmcnt(1)
	v_mfma_f32_32x32x16_bf16 v[112:127], v[2:5], v[160:163], v[112:127]
	ds_read_b128 v[2:5], v0 offset:13056
	ds_read_b128 v[10:13], v0 offset:13088
	s_waitcnt lgkmcnt(1)
	v_mfma_f32_32x32x16_bf16 v[96:111], v[2:5], v[160:163], v[96:111]
	v_mfma_f32_32x32x16_bf16 v[112:127], v[6:9], v[164:167], v[112:127]
	ds_read_b128 v[2:5], v0 offset:320
	ds_read_b128 v[6:9], v0 offset:352
	s_waitcnt lgkmcnt(2)
	v_mfma_f32_32x32x16_bf16 v[96:111], v[10:13], v[164:167], v[96:111]
	s_waitcnt lgkmcnt(1)
	v_mfma_f32_32x32x16_bf16 v[112:127], v[2:5], v[168:171], v[112:127]
	ds_read_b128 v[2:5], v0 offset:13120
	ds_read_b128 v[10:13], v0 offset:13152
	s_waitcnt lgkmcnt(1)
	v_mfma_f32_32x32x16_bf16 v[96:111], v[2:5], v[168:171], v[96:111]
	v_lshl_add_u64 v[2:3], v[206:207], 0, s[8:9]
	v_lshl_add_u64 v[4:5], v[218:219], 0, s[8:9]
	v_mfma_f32_32x32x16_bf16 v[112:127], v[6:9], v[172:175], v[112:127]
	global_load_dwordx4 v[6:9], v[2:3], off
	s_nop 0
	global_load_dwordx4 v[2:5], v[4:5], off
	s_waitcnt lgkmcnt(0)
	v_mfma_f32_32x32x16_bf16 v[96:111], v[10:13], v[172:175], v[96:111]
	s_add_i32 s8, s75, 0
	s_add_i32 s8, s8, 0x12c00
	v_add_u32_e32 v0, s8, v227
	v_add_u32_e32 v221, v0, v226
	ds_read2_b64 v[10:13], v221 offset1:2
	v_add_u32_e32 v0, s58, v225
	v_add_u32_e32 v220, 0x1000, v221
	ds_read2_b64 v[236:239], v220 offset0:32 offset1:34
	s_waitcnt lgkmcnt(1)
	v_mfma_f32_32x32x16_bf16 v[64:79], v[10:13], v[200:203], v[64:79]
	v_add_u32_e32 v10, 0xffffffa0, v0
	v_cmp_le_i32_e32 vcc, v10, v216
	v_subrev_u32_e32 v12, 64, v0
	s_nop 0
	v_cndmask_b32_e32 v11, v224, v112, vcc
	v_cmp_le_i32_e32 vcc, v12, v216
	v_max_f32_e32 v12, v11, v11
	v_max_f32_e32 v12, 0xff800000, v12
	v_cndmask_b32_e32 v231, v224, v96, vcc
	v_cmp_lt_i32_e32 vcc, v10, v216
	v_subrev_u32_e32 v10, 63, v0
	s_nop 0
	v_cndmask_b32_e32 v233, v11, v112, vcc
	v_cndmask_b32_e32 v232, v224, v113, vcc
	v_cmp_le_i32_e32 vcc, v10, v216
	v_add_u32_e32 v11, 0xffffffa2, v0
	s_nop 0
	v_cndmask_b32_e32 v234, v224, v97, vcc
	v_cmp_le_i32_e32 vcc, v11, v216
	v_subrev_u32_e32 v11, 62, v0
	v_max3_f32 v10, v231, s64, v234
	v_cndmask_b32_e32 v14, v224, v114, vcc
	v_cmp_le_i32_e32 vcc, v11, v216
	v_add_u32_e32 v11, 0xffffffa3, v0
	s_nop 0
	v_cndmask_b32_e32 v96, v224, v98, vcc
	v_cmp_le_i32_e32 vcc, v11, v216
	v_subrev_u32_e32 v11, 61, v0
	v_max3_f32 v98, v12, v232, v14
	v_cndmask_b32_e32 v15, v224, v115, vcc
	v_cmp_le_i32_e32 vcc, v11, v216
	s_nop 1
	v_cndmask_b32_e32 v97, v224, v99, vcc
	v_max3_f32 v99, v10, v96, v97
	v_add_u32_e32 v112, 0xffffffa8, v0
	v_cmp_le_i32_e32 vcc, v112, v216
	v_subrev_u32_e32 v113, 56, v0
	s_waitcnt lgkmcnt(0)
	v_mfma_f32_32x32x16_bf16 v[48:63], v[236:239], v[200:203], v[48:63]
	v_cndmask_b32_e32 v112, v224, v116, vcc
	v_cmp_le_i32_e32 vcc, v113, v216
	v_max3_f32 v114, v98, v15, v112
	v_add_u32_e32 v98, 0xffffffa9, v0
	v_cndmask_b32_e32 v116, v224, v100, vcc
	v_cmp_le_i32_e32 vcc, v98, v216
	v_subrev_u32_e32 v98, 55, v0
	v_add_u32_e32 v229, 0x2000, v221
	v_cndmask_b32_e32 v113, v224, v117, vcc
	v_cmp_le_i32_e32 vcc, v98, v216
	v_add_u32_e32 v98, 0xffffffaa, v0
	ds_read2_b64 v[10:13], v229 offset0:64 offset1:66
	v_cndmask_b32_e32 v117, v224, v101, vcc
	v_max3_f32 v115, v99, v116, v117
	v_cmp_le_i32_e32 vcc, v98, v216
	v_subrev_u32_e32 v99, 54, v0
	v_subrev_u32_e32 v101, 53, v0
	v_cndmask_b32_e32 v98, v224, v118, vcc
	v_cmp_le_i32_e32 vcc, v99, v216
	v_add_u32_e32 v99, 0xffffffab, v0
	s_nop 0
	v_cndmask_b32_e32 v100, v224, v102, vcc
	v_cmp_le_i32_e32 vcc, v99, v216
	v_max3_f32 v102, v114, v113, v98
	s_nop 0
	v_cndmask_b32_e32 v99, v224, v119, vcc
	v_cmp_le_i32_e32 vcc, v101, v216
	s_nop 1
	v_cndmask_b32_e32 v101, v224, v103, vcc
	v_max3_f32 v103, v115, v100, v101
	s_waitcnt lgkmcnt(0)
	v_mfma_f32_32x32x16_bf16 v[32:47], v[10:13], v[200:203], v[32:47]
	v_add_u32_e32 v10, 0xffffffb0, v0
	v_cmp_le_i32_e32 vcc, v10, v216
	v_subrev_u32_e32 v10, 48, v0
	v_add_u32_e32 v11, 0xffffffb1, v0
	v_cndmask_b32_e32 v114, v224, v120, vcc
	v_cmp_le_i32_e32 vcc, v10, v216
	v_add_u32_e32 v12, 0xffffffb2, v0
	v_add_u32_e32 v230, 0x3000, v221
	v_cndmask_b32_e32 v118, v224, v104, vcc
	v_cmp_le_i32_e32 vcc, v11, v216
	v_subrev_u32_e32 v11, 47, v0
	v_max3_f32 v10, v102, v99, v114
	v_cndmask_b32_e32 v115, v224, v121, vcc
	v_cmp_le_i32_e32 vcc, v11, v216
	ds_read2_b64 v[236:239], v230 offset0:96 offset1:98
	s_nop 0
	v_cndmask_b32_e32 v119, v224, v105, vcc
	v_cmp_le_i32_e32 vcc, v12, v216
	v_subrev_u32_e32 v12, 46, v0
	v_max3_f32 v11, v103, v118, v119
	v_cndmask_b32_e32 v102, v224, v122, vcc
	v_cmp_le_i32_e32 vcc, v12, v216
	v_add_u32_e32 v12, 0xffffffb3, v0
	v_max3_f32 v10, v10, v115, v102
	v_cndmask_b32_e32 v104, v224, v106, vcc
	v_cmp_le_i32_e32 vcc, v12, v216
	v_subrev_u32_e32 v12, 45, v0
	s_nop 0
	v_cndmask_b32_e32 v103, v224, v123, vcc
	v_cmp_le_i32_e32 vcc, v12, v216
	s_nop 1
	v_cndmask_b32_e32 v105, v224, v107, vcc
	v_max3_f32 v11, v11, v104, v105
	v_add_u32_e32 v12, 0xffffffb8, v0
	v_cmp_le_i32_e32 vcc, v12, v216
	v_subrev_u32_e32 v12, 40, v0
	s_waitcnt lgkmcnt(0)
	v_mfma_f32_32x32x16_bf16 v[16:31], v[236:239], v[200:203], v[16:31]
	v_cndmask_b32_e32 v106, v224, v124, vcc
	v_cmp_le_i32_e32 vcc, v12, v216
	v_add_u32_e32 v12, 0xffffffb9, v0
	v_max3_f32 v10, v10, v103, v106
	v_cndmask_b32_e32 v120, v224, v108, vcc
	v_cmp_le_i32_e32 vcc, v12, v216
	v_subrev_u32_e32 v12, 39, v0
	ds_read2_b64 v[240:243], v221 offset0:4 offset1:6
	v_cndmask_b32_e32 v107, v224, v125, vcc
	v_cmp_le_i32_e32 vcc, v12, v216
	v_add_u32_e32 v12, 0xffffffba, v0
	s_nop 0
	v_cndmask_b32_e32 v121, v224, v109, vcc
	v_cmp_le_i32_e32 vcc, v12, v216
	v_subrev_u32_e32 v12, 38, v0
	v_max3_f32 v11, v11, v120, v121
	v_cndmask_b32_e32 v124, v224, v126, vcc
	v_cmp_le_i32_e32 vcc, v12, v216
	s_nop 1
	v_cndmask_b32_e32 v125, v224, v110, vcc
	v_max3_f32 v110, v10, v107, v124
	v_add_u32_e32 v10, 0xffffffbb, v0
	v_cmp_le_i32_e32 vcc, v10, v216
	v_subrev_u32_e32 v0, 37, v0
	s_nop 0
	v_cndmask_b32_e32 v108, v224, v127, vcc
	v_cmp_le_i32_e32 vcc, v0, v216
	s_nop 1
	v_cndmask_b32_e32 v109, v224, v111, vcc
	v_max3_f32 v0, v11, v125, v109
	v_max3_f32 v0, v110, v108, v0
	v_mov_b32_e32 v110, v0
	ds_read2_b64 v[10:13], v220 offset0:36 offset1:38
	s_waitcnt lgkmcnt(1)
	v_mfma_f32_32x32x16_bf16 v[64:79], v[240:243], v[196:199], v[64:79]
	v_permlane32_swap_b32_e32 v110, v0
	v_max_f32_e32 v110, v110, v110
	v_max_f32_e32 v0, v0, v110
	v_cmp_lt_f32_e32 vcc, s65, v0
	s_cbranch_vccz .LBB0_626
	v_max_f32_e32 v0, v0, v0
	v_max_f32_e32 v0, 0, v0
	v_add_f32_e32 v217, v217, v0
	v_sub_f32_e32 v233, v233, v0
	v_sub_f32_e32 v232, v232, v0
	v_sub_f32_e32 v231, v231, v0
	v_sub_f32_e32 v234, v234, v0
	v_pk_add_f32 v[14:15], v[14:15], v[0:1] op_sel_hi:[1,0] neg_lo:[0,1] neg_hi:[0,1]
	v_pk_add_f32 v[96:97], v[96:97], v[0:1] op_sel_hi:[1,0] neg_lo:[0,1] neg_hi:[0,1]
	v_pk_add_f32 v[112:113], v[112:113], v[0:1] op_sel_hi:[1,0] neg_lo:[0,1] neg_hi:[0,1]
	v_pk_add_f32 v[116:117], v[116:117], v[0:1] op_sel_hi:[1,0] neg_lo:[0,1] neg_hi:[0,1]
	v_pk_add_f32 v[98:99], v[98:99], v[0:1] op_sel_hi:[1,0] neg_lo:[0,1] neg_hi:[0,1]
	v_pk_add_f32 v[100:101], v[100:101], v[0:1] op_sel_hi:[1,0] neg_lo:[0,1] neg_hi:[0,1]
	v_pk_add_f32 v[114:115], v[114:115], v[0:1] op_sel_hi:[1,0] neg_lo:[0,1] neg_hi:[0,1]
	v_pk_add_f32 v[118:119], v[118:119], v[0:1] op_sel_hi:[1,0] neg_lo:[0,1] neg_hi:[0,1]
	v_pk_add_f32 v[102:103], v[102:103], v[0:1] op_sel_hi:[1,0] neg_lo:[0,1] neg_hi:[0,1]
	v_pk_add_f32 v[104:105], v[104:105], v[0:1] op_sel_hi:[1,0] neg_lo:[0,1] neg_hi:[0,1]
	v_pk_add_f32 v[106:107], v[106:107], v[0:1] op_sel_hi:[1,0] neg_lo:[0,1] neg_hi:[0,1]
	v_pk_add_f32 v[120:121], v[120:121], v[0:1] op_sel_hi:[1,0] neg_lo:[0,1] neg_hi:[0,1]
	v_sub_f32_e32 v124, v124, v0
	v_sub_f32_e32 v125, v125, v0
	v_pk_add_f32 v[108:109], v[108:109], v[0:1] op_sel_hi:[1,0] neg_lo:[0,1] neg_hi:[0,1]
	v_exp_f32_e64 v0, -v0
	v_xor_b32_e32 v80, 0x80000000, v217
	v_mov_b32_e32 v81, v80
	v_mov_b32_e32 v82, v80
	v_mov_b32_e32 v83, v80
	v_mov_b32_e32 v84, v80
	v_mov_b32_e32 v85, v80
	v_mov_b32_e32 v86, v80
	v_mov_b32_e32 v87, v80
	v_mov_b32_e32 v88, v80
	v_mov_b32_e32 v89, v80
	v_mov_b32_e32 v90, v80
	v_mov_b32_e32 v91, v80
	v_mov_b32_e32 v92, v80
	v_mov_b32_e32 v93, v80
	v_mov_b32_e32 v94, v80
	v_mov_b32_e32 v95, v80
	s_branch .LBB0_627

.LBB0_627:
	s_waitcnt lgkmcnt(0)
	v_mfma_f32_32x32x16_bf16 v[48:63], v[10:13], v[196:199], v[48:63]
	ds_read2_b64 v[200:203], v229 offset0:68 offset1:70
	v_exp_f32_e32 v12, v233
	v_exp_f32_e32 v13, v231
	v_exp_f32_e32 v10, v232
	v_exp_f32_e32 v11, v234
	s_waitcnt lgkmcnt(0)
	v_mfma_f32_32x32x16_bf16 v[32:47], v[200:203], v[196:199], v[32:47]
	ds_read2_b64 v[232:235], v230 offset0:100 offset1:102
	v_exp_f32_e32 v110, v14
	v_exp_f32_e32 v111, v96
	v_exp_f32_e32 v14, v15
	v_exp_f32_e32 v15, v97
	s_waitcnt lgkmcnt(0)
	v_mfma_f32_32x32x16_bf16 v[16:31], v[232:235], v[196:199], v[16:31]
	ds_read2_b64 v[200:203], v221 offset0:8 offset1:10
	v_exp_f32_e32 v122, v112
	v_exp_f32_e32 v123, v116
	v_exp_f32_e32 v96, v113
	v_exp_f32_e32 v97, v117
	s_waitcnt lgkmcnt(0)
	v_mfma_f32_32x32x16_bf16 v[64:79], v[200:203], v[192:195], v[64:79]
	ds_read2_b64 v[196:199], v220 offset0:40 offset1:42
	v_exp_f32_e32 v112, v98
	v_exp_f32_e32 v113, v100
	v_exp_f32_e32 v98, v99
	v_exp_f32_e32 v99, v101
	s_waitcnt lgkmcnt(0)
	v_mfma_f32_32x32x16_bf16 v[48:63], v[196:199], v[192:195], v[48:63]
	ds_read2_b64 v[200:203], v229 offset0:72 offset1:74
	v_exp_f32_e32 v116, v114
	v_exp_f32_e32 v117, v118
	v_exp_f32_e32 v100, v115
	v_exp_f32_e32 v101, v119
	s_waitcnt lgkmcnt(0)
	v_mfma_f32_32x32x16_bf16 v[32:47], v[200:203], v[192:195], v[32:47]
	ds_read2_b64 v[196:199], v230 offset0:104 offset1:106
	v_exp_f32_e32 v114, v102
	v_exp_f32_e32 v115, v104
	v_exp_f32_e32 v102, v103
	v_exp_f32_e32 v103, v105
	s_waitcnt lgkmcnt(0)
	v_mfma_f32_32x32x16_bf16 v[16:31], v[196:199], v[192:195], v[16:31]
	ds_read2_b64 v[200:203], v221 offset0:12 offset1:14
	v_exp_f32_e32 v118, v106
	v_exp_f32_e32 v119, v120
	v_exp_f32_e32 v104, v107
	v_exp_f32_e32 v105, v121
	s_waitcnt lgkmcnt(0)
	v_mfma_f32_32x32x16_bf16 v[64:79], v[200:203], v[180:183], v[64:79]
	ds_read2_b64 v[192:195], v220 offset0:44 offset1:46
	v_exp_f32_e32 v120, v124
	v_exp_f32_e32 v121, v125
	v_exp_f32_e32 v106, v108
	v_exp_f32_e32 v107, v109
	s_waitcnt lgkmcnt(0)
	v_mfma_f32_32x32x16_bf16 v[48:63], v[192:195], v[180:183], v[48:63]
	ds_read2_b64 v[124:127], v229 offset0:76 offset1:78
	v_cvt_pk_bf16_f32 v200, v12, v10
	v_cvt_pk_bf16_f32 v201, v110, v14
	v_cvt_pk_bf16_f32 v202, v122, v96
	v_cvt_pk_bf16_f32 v203, v112, v98
	v_cvt_pk_bf16_f32 v196, v116, v100
	v_cvt_pk_bf16_f32 v197, v114, v102
	v_cvt_pk_bf16_f32 v198, v118, v104
	v_cvt_pk_bf16_f32 v199, v120, v106
	s_waitcnt lgkmcnt(0)
	v_mfma_f32_32x32x16_bf16 v[32:47], v[124:127], v[180:183], v[32:47]
	ds_read2_b64 v[230:233], v230 offset0:108 offset1:110
	v_cvt_pk_bf16_f32 v192, v13, v11
	v_cvt_pk_bf16_f32 v193, v111, v15
	v_cvt_pk_bf16_f32 v194, v123, v97
	v_cvt_pk_bf16_f32 v195, v113, v99
	s_waitcnt lgkmcnt(0)
	v_mfma_f32_32x32x16_bf16 v[16:31], v[230:233], v[180:183], v[16:31]
	v_cvt_pk_bf16_f32 v180, v117, v101
	v_cvt_pk_bf16_f32 v181, v115, v103
	v_cvt_pk_bf16_f32 v182, v119, v105
	v_cvt_pk_bf16_f32 v183, v121, v107
	v_cmp_gt_f32_e32 vcc, 1.0, v0
	s_cbranch_vccz .LBB0_629
	v_pk_mul_f32 v[78:79], v[0:1], v[78:79] op_sel_hi:[0,1]
	v_pk_mul_f32 v[76:77], v[0:1], v[76:77] op_sel_hi:[0,1]
	v_pk_mul_f32 v[74:75], v[0:1], v[74:75] op_sel_hi:[0,1]
	v_pk_mul_f32 v[72:73], v[0:1], v[72:73] op_sel_hi:[0,1]
	v_pk_mul_f32 v[70:71], v[0:1], v[70:71] op_sel_hi:[0,1]
	v_pk_mul_f32 v[68:69], v[0:1], v[68:69] op_sel_hi:[0,1]
	v_pk_mul_f32 v[66:67], v[0:1], v[66:67] op_sel_hi:[0,1]
	v_pk_mul_f32 v[64:65], v[0:1], v[64:65] op_sel_hi:[0,1]
	v_pk_mul_f32 v[62:63], v[0:1], v[62:63] op_sel_hi:[0,1]
	v_pk_mul_f32 v[60:61], v[0:1], v[60:61] op_sel_hi:[0,1]
	v_pk_mul_f32 v[58:59], v[0:1], v[58:59] op_sel_hi:[0,1]
	v_pk_mul_f32 v[56:57], v[0:1], v[56:57] op_sel_hi:[0,1]
	v_pk_mul_f32 v[54:55], v[0:1], v[54:55] op_sel_hi:[0,1]
	v_pk_mul_f32 v[52:53], v[0:1], v[52:53] op_sel_hi:[0,1]
	v_pk_mul_f32 v[50:51], v[0:1], v[50:51] op_sel_hi:[0,1]
	v_pk_mul_f32 v[48:49], v[0:1], v[48:49] op_sel_hi:[0,1]
	v_pk_mul_f32 v[46:47], v[0:1], v[46:47] op_sel_hi:[0,1]
	v_pk_mul_f32 v[44:45], v[0:1], v[44:45] op_sel_hi:[0,1]
	v_pk_mul_f32 v[42:43], v[0:1], v[42:43] op_sel_hi:[0,1]
	v_pk_mul_f32 v[40:41], v[0:1], v[40:41] op_sel_hi:[0,1]
	v_pk_mul_f32 v[38:39], v[0:1], v[38:39] op_sel_hi:[0,1]
	v_pk_mul_f32 v[36:37], v[0:1], v[36:37] op_sel_hi:[0,1]
	v_pk_mul_f32 v[34:35], v[0:1], v[34:35] op_sel_hi:[0,1]
	v_pk_mul_f32 v[32:33], v[0:1], v[32:33] op_sel_hi:[0,1]
	v_pk_mul_f32 v[30:31], v[0:1], v[30:31] op_sel_hi:[0,1]
	v_pk_mul_f32 v[28:29], v[0:1], v[28:29] op_sel_hi:[0,1]
	v_pk_mul_f32 v[26:27], v[0:1], v[26:27] op_sel_hi:[0,1]
	v_pk_mul_f32 v[24:25], v[0:1], v[24:25] op_sel_hi:[0,1]
	v_pk_mul_f32 v[22:23], v[0:1], v[22:23] op_sel_hi:[0,1]
	v_pk_mul_f32 v[20:21], v[0:1], v[20:21] op_sel_hi:[0,1]
	v_pk_mul_f32 v[18:19], v[0:1], v[18:19] op_sel_hi:[0,1]
	v_pk_mul_f32 v[16:17], v[0:1], v[16:17] op_sel_hi:[0,1]

.LBB0_1177:
	s_sub_i32 s6, s36, 32
	s_lshl_b64 s[62:63], s[6:7], 11
	s_mov_b32 s37, s7
	v_lshl_add_u64 v[232:233], v[208:209], 0, s[62:63]
	s_lshl_b64 s[62:63], s[36:37], 11
	global_load_dwordx4 v[176:179], v[232:233], off
	v_lshl_add_u64 v[232:233], v[208:209], 0, s[62:63]
	s_lshl_b64 s[62:63], s[6:7], 7
	global_load_dwordx4 v[180:183], v[232:233], off
	v_lshl_add_u64 v[232:233], v[210:211], 0, s[62:63]
	global_load_dwordx4 v[184:187], v[232:233], off
	v_add_u32_e32 v0, s38, v215
	ds_read_b128 v[2:5], v0
	ds_read_b128 v[6:9], v0 offset:32
	v_mov_b64_e32 v[126:127], v[94:95]
	v_mov_b64_e32 v[124:125], v[92:93]
	v_mov_b64_e32 v[122:123], v[90:91]
	s_waitcnt lgkmcnt(1)
	v_mfma_f32_32x32x16_bf16 v[96:111], v[2:5], v[128:131], v[80:95]
	ds_read_b128 v[2:5], v0 offset:12800
	ds_read_b128 v[10:13], v0 offset:12832
	v_mov_b64_e32 v[120:121], v[88:89]
	v_mov_b64_e32 v[118:119], v[86:87]
	v_mov_b64_e32 v[116:117], v[84:85]
	v_mov_b64_e32 v[114:115], v[82:83]
	v_mov_b64_e32 v[112:113], v[80:81]
	s_waitcnt lgkmcnt(2)
	v_mfma_f32_32x32x16_bf16 v[96:111], v[6:9], v[132:135], v[96:111]
	s_mov_b32 s58, s59
	s_mov_b32 s59, s60
	s_waitcnt lgkmcnt(1)
	v_mfma_f32_32x32x16_bf16 v[112:127], v[2:5], v[128:131], v[112:127]
	ds_read_b128 v[2:5], v0 offset:64
	ds_read_b128 v[6:9], v0 offset:96
	s_waitcnt lgkmcnt(2)
	v_mfma_f32_32x32x16_bf16 v[112:127], v[10:13], v[132:135], v[112:127]
	s_waitcnt lgkmcnt(1)
	v_mfma_f32_32x32x16_bf16 v[96:111], v[2:5], v[136:139], v[96:111]
	ds_read_b128 v[2:5], v0 offset:12864
	ds_read_b128 v[10:13], v0 offset:12896
	s_waitcnt lgkmcnt(1)
	v_mfma_f32_32x32x16_bf16 v[112:127], v[2:5], v[136:139], v[112:127]
	v_mfma_f32_32x32x16_bf16 v[96:111], v[6:9], v[140:143], v[96:111]
	ds_read_b128 v[2:5], v0 offset:128
	ds_read_b128 v[6:9], v0 offset:160
	s_waitcnt lgkmcnt(2)
	v_mfma_f32_32x32x16_bf16 v[112:127], v[10:13], v[140:143], v[112:127]
	s_waitcnt lgkmcnt(1)
	v_mfma_f32_32x32x16_bf16 v[96:111], v[2:5], v[144:147], v[96:111]
	ds_read_b128 v[2:5], v0 offset:12928
	ds_read_b128 v[10:13], v0 offset:12960
	s_waitcnt lgkmcnt(1)
	v_mfma_f32_32x32x16_bf16 v[112:127], v[2:5], v[144:147], v[112:127]
	v_mfma_f32_32x32x16_bf16 v[96:111], v[6:9], v[148:151], v[96:111]
	ds_read_b128 v[2:5], v0 offset:192
	ds_read_b128 v[6:9], v0 offset:224
	s_waitcnt lgkmcnt(2)
	v_mfma_f32_32x32x16_bf16 v[112:127], v[10:13], v[148:151], v[112:127]
	s_waitcnt lgkmcnt(1)
	v_mfma_f32_32x32x16_bf16 v[96:111], v[2:5], v[152:155], v[96:111]
	ds_read_b128 v[2:5], v0 offset:12992
	ds_read_b128 v[10:13], v0 offset:13024
	s_waitcnt lgkmcnt(1)
	v_mfma_f32_32x32x16_bf16 v[112:127], v[2:5], v[152:155], v[112:127]
	v_mfma_f32_32x32x16_bf16 v[96:111], v[6:9], v[156:159], v[96:111]
	ds_read_b128 v[2:5], v0 offset:256
	ds_read_b128 v[6:9], v0 offset:288
	s_waitcnt lgkmcnt(2)
	v_mfma_f32_32x32x16_bf16 v[112:127], v[10:13], v[156:159], v[112:127]
	s_waitcnt lgkmcnt(1)
	v_mfma_f32_32x32x16_bf16 v[96:111], v[2:5], v[160:163], v[96:111]
	ds_read_b128 v[2:5], v0 offset:13056
	ds_read_b128 v[10:13], v0 offset:13088
	s_waitcnt lgkmcnt(1)
	v_mfma_f32_32x32x16_bf16 v[112:127], v[2:5], v[160:163], v[112:127]
	ds_read_b128 v[2:5], v0 offset:320
	v_mfma_f32_32x32x16_bf16 v[96:111], v[6:9], v[164:167], v[96:111]
	s_waitcnt lgkmcnt(1)
	v_mfma_f32_32x32x16_bf16 v[112:127], v[10:13], v[164:167], v[112:127]
	ds_read_b128 v[6:9], v0 offset:13120
	ds_read_b128 v[10:13], v0 offset:352
	s_waitcnt lgkmcnt(2)
	v_mfma_f32_32x32x16_bf16 v[96:111], v[2:5], v[168:171], v[96:111]
	s_add_i32 s6, s36, 0xffffffa0
	ds_read_b128 v[230:233], v0 offset:13152
	s_waitcnt lgkmcnt(2)
	v_mfma_f32_32x32x16_bf16 v[112:127], v[6:9], v[168:171], v[112:127]
	s_lshl_b64 s[62:63], s[6:7], 1
	v_lshl_add_u64 v[8:9], v[218:219], 0, s[62:63]
	v_lshl_add_u64 v[2:3], v[206:207], 0, s[62:63]
	global_load_dwordx4 v[2:5], v[2:3], off
	s_nop 0
	s_nop 0
	global_load_dwordx4 v[6:9], v[8:9], off
	s_waitcnt lgkmcnt(1)
	v_mfma_f32_32x32x16_bf16 v[96:111], v[10:13], v[172:175], v[96:111]
	s_waitcnt lgkmcnt(0)
	v_mfma_f32_32x32x16_bf16 v[112:127], v[230:233], v[172:175], v[112:127]
	s_add_i32 s6, s58, 0
	s_add_i32 s6, s6, 0x12c00
	v_add_u32_e32 v0, s6, v227
	v_add_u32_e32 v231, v0, v226
	v_add_u32_e32 v229, 0x1000, v231
	v_add_u32_e32 v230, 0x2000, v231
	v_add_u32_e32 v252, 0x3000, v231
	ds_read2_b64 v[234:237], v231 offset1:2
	ds_read2_b64 v[238:241], v229 offset0:32 offset1:34
	ds_read2_b64 v[244:247], v230 offset0:64 offset1:66
	ds_read2_b64 v[248:251], v252 offset0:96 offset1:98
	s_nop 2
	v_max_f32_e32 v0, v96, v96
	v_max_f32_e32 v0, 0xff800000, v0
	v_max3_f32 v0, v0, v97, v98
	s_waitcnt lgkmcnt(3)
	v_mfma_f32_32x32x16_bf16 v[64:79], v[234:237], v[200:203], v[64:79]
	ds_read2_b64 v[234:237], v231 offset0:4 offset1:6
	v_max3_f32 v10, v112, s52, v113
	v_max3_f32 v14, v10, v114, v115
	s_waitcnt lgkmcnt(3)
	v_mfma_f32_32x32x16_bf16 v[48:63], v[238:241], v[200:203], v[48:63]
	ds_read2_b64 v[238:241], v229 offset0:36 offset1:38
	v_max3_f32 v0, v0, v99, v100
	v_max3_f32 v14, v14, v116, v117
	v_max3_f32 v0, v0, v101, v102
	v_max3_f32 v14, v14, v118, v119
	s_waitcnt lgkmcnt(3)
	v_mfma_f32_32x32x16_bf16 v[32:47], v[244:247], v[200:203], v[32:47]
	ds_read2_b64 v[244:247], v230 offset0:68 offset1:70
	v_max3_f32 v0, v0, v103, v104
	v_max3_f32 v14, v14, v120, v121
	v_max3_f32 v0, v0, v105, v106
	v_max3_f32 v14, v14, v122, v123
	s_waitcnt lgkmcnt(3)
	v_mfma_f32_32x32x16_bf16 v[16:31], v[248:251], v[200:203], v[16:31]
	ds_read2_b64 v[248:251], v252 offset0:100 offset1:102
	v_max3_f32 v0, v0, v107, v108
	v_max3_f32 v10, v14, v124, v125
	v_max3_f32 v0, v0, v109, v110
	v_max3_f32 v14, v10, v126, v127
	v_max3_f32 v0, v0, v111, v14
	v_mov_b32_e32 v14, v0
	s_waitcnt lgkmcnt(3)
	v_mfma_f32_32x32x16_bf16 v[64:79], v[234:237], v[196:199], v[64:79]
	ds_read2_b64 v[234:237], v231 offset0:8 offset1:10
	v_permlane32_swap_b32_e32 v14, v0
	v_max_f32_e32 v14, v14, v14
	v_max_f32_e32 v0, v0, v14
	v_cmp_lt_f32_e32 vcc, s53, v0
	s_cbranch_vccz .LBB0_1179
	v_max_f32_e32 v0, v0, v0
	v_max_f32_e32 v0, 0, v0
	v_add_f32_e32 v217, v217, v0
	v_pk_add_f32 v[96:97], v[96:97], v[0:1] op_sel_hi:[1,0] neg_lo:[0,1] neg_hi:[0,1]
	v_pk_add_f32 v[112:113], v[112:113], v[0:1] op_sel_hi:[1,0] neg_lo:[0,1] neg_hi:[0,1]
	v_pk_add_f32 v[98:99], v[98:99], v[0:1] op_sel_hi:[1,0] neg_lo:[0,1] neg_hi:[0,1]
	v_pk_add_f32 v[114:115], v[114:115], v[0:1] op_sel_hi:[1,0] neg_lo:[0,1] neg_hi:[0,1]
	v_pk_add_f32 v[100:101], v[100:101], v[0:1] op_sel_hi:[1,0] neg_lo:[0,1] neg_hi:[0,1]
	v_pk_add_f32 v[116:117], v[116:117], v[0:1] op_sel_hi:[1,0] neg_lo:[0,1] neg_hi:[0,1]
	v_pk_add_f32 v[102:103], v[102:103], v[0:1] op_sel_hi:[1,0] neg_lo:[0,1] neg_hi:[0,1]
	v_pk_add_f32 v[118:119], v[118:119], v[0:1] op_sel_hi:[1,0] neg_lo:[0,1] neg_hi:[0,1]
	v_pk_add_f32 v[104:105], v[104:105], v[0:1] op_sel_hi:[1,0] neg_lo:[0,1] neg_hi:[0,1]
	v_pk_add_f32 v[120:121], v[120:121], v[0:1] op_sel_hi:[1,0] neg_lo:[0,1] neg_hi:[0,1]
	v_pk_add_f32 v[106:107], v[106:107], v[0:1] op_sel_hi:[1,0] neg_lo:[0,1] neg_hi:[0,1]
	v_pk_add_f32 v[122:123], v[122:123], v[0:1] op_sel_hi:[1,0] neg_lo:[0,1] neg_hi:[0,1]
	v_pk_add_f32 v[108:109], v[108:109], v[0:1] op_sel_hi:[1,0] neg_lo:[0,1] neg_hi:[0,1]
	v_pk_add_f32 v[124:125], v[124:125], v[0:1] op_sel_hi:[1,0] neg_lo:[0,1] neg_hi:[0,1]
	v_pk_add_f32 v[110:111], v[110:111], v[0:1] op_sel_hi:[1,0] neg_lo:[0,1] neg_hi:[0,1]
	v_pk_add_f32 v[126:127], v[126:127], v[0:1] op_sel_hi:[1,0] neg_lo:[0,1] neg_hi:[0,1]
	v_exp_f32_e64 v0, -v0
	v_xor_b32_e32 v80, 0x80000000, v217
	v_mov_b32_e32 v81, v80
	v_mov_b32_e32 v82, v80
	v_mov_b32_e32 v83, v80
	v_mov_b32_e32 v84, v80
	v_mov_b32_e32 v85, v80
	v_mov_b32_e32 v86, v80
	v_mov_b32_e32 v87, v80
	v_mov_b32_e32 v88, v80
	v_mov_b32_e32 v89, v80
	v_mov_b32_e32 v90, v80
	v_mov_b32_e32 v91, v80
	v_mov_b32_e32 v92, v80
	v_mov_b32_e32 v93, v80
	v_mov_b32_e32 v94, v80
	v_mov_b32_e32 v95, v80
	s_branch .LBB0_1180

.LBB0_1180:
	s_waitcnt lgkmcnt(3)
	v_mfma_f32_32x32x16_bf16 v[48:63], v[238:241], v[196:199], v[48:63]
	ds_read2_b64 v[238:241], v229 offset0:40 offset1:42
	v_add_u32_e32 v232, s57, v212
	v_add_u32_e32 v233, s57, v214
	s_waitcnt vmcnt(4)
	ds_write_b128 v232, v[176:179]
	v_exp_f32_e32 v220, v96
	v_exp_f32_e32 v221, v112
	v_exp_f32_e32 v14, v97
	v_exp_f32_e32 v15, v113
	s_waitcnt lgkmcnt(4)
	v_mfma_f32_32x32x16_bf16 v[32:47], v[244:247], v[196:199], v[32:47]
	ds_read2_b64 v[244:247], v230 offset0:72 offset1:74
	s_waitcnt vmcnt(3)
	ds_write_b128 v232, v[180:183] offset:12800
	v_exp_f32_e32 v12, v98
	v_exp_f32_e32 v13, v114
	v_exp_f32_e32 v10, v99
	v_exp_f32_e32 v11, v115
	s_waitcnt lgkmcnt(5)
	v_mfma_f32_32x32x16_bf16 v[16:31], v[248:251], v[196:199], v[16:31]
	ds_read2_b64 v[248:251], v252 offset0:104 offset1:106
	s_waitcnt vmcnt(2)
	ds_write_b128 v233, v[184:187] offset:256
	v_exp_f32_e32 v98, v100
	v_exp_f32_e32 v99, v116
	v_exp_f32_e32 v96, v101
	v_exp_f32_e32 v97, v117
	s_waitcnt lgkmcnt(6)
	v_mfma_f32_32x32x16_bf16 v[64:79], v[234:237], v[192:195], v[64:79]
	ds_read2_b64 v[234:237], v231 offset0:12 offset1:14
	v_exp_f32_e32 v112, v102
	v_exp_f32_e32 v113, v118
	v_exp_f32_e32 v100, v103
	v_exp_f32_e32 v101, v119
	s_waitcnt lgkmcnt(6)
	v_mfma_f32_32x32x16_bf16 v[48:63], v[238:241], v[192:195], v[48:63]
	ds_read2_b64 v[238:241], v229 offset0:44 offset1:46
	v_exp_f32_e32 v114, v104
	v_exp_f32_e32 v115, v120
	v_exp_f32_e32 v102, v105
	v_exp_f32_e32 v103, v121
	s_waitcnt lgkmcnt(5)
	v_mfma_f32_32x32x16_bf16 v[32:47], v[244:247], v[192:195], v[32:47]
	ds_read2_b64 v[244:247], v230 offset0:76 offset1:78
	v_exp_f32_e32 v116, v106
	v_exp_f32_e32 v117, v122
	v_exp_f32_e32 v104, v107
	v_exp_f32_e32 v105, v123
	s_waitcnt lgkmcnt(4)
	v_mfma_f32_32x32x16_bf16 v[16:31], v[248:251], v[192:195], v[16:31]
	ds_read2_b64 v[248:251], v252 offset0:108 offset1:110
	v_exp_f32_e32 v118, v108
	v_exp_f32_e32 v119, v124
	v_exp_f32_e32 v106, v109
	v_exp_f32_e32 v107, v125
	s_waitcnt lgkmcnt(3)
	v_mfma_f32_32x32x16_bf16 v[64:79], v[234:237], v[188:191], v[64:79]
	v_exp_f32_e32 v120, v110
	v_exp_f32_e32 v121, v126
	v_exp_f32_e32 v108, v111
	v_exp_f32_e32 v109, v127
	s_waitcnt lgkmcnt(2)
	v_mfma_f32_32x32x16_bf16 v[48:63], v[238:241], v[188:191], v[48:63]
	v_cvt_pk_bf16_f32 v200, v220, v14
	v_cvt_pk_bf16_f32 v201, v12, v10
	v_cvt_pk_bf16_f32 v202, v98, v96
	v_cvt_pk_bf16_f32 v203, v112, v100
	v_cvt_pk_bf16_f32 v196, v114, v102
	v_cvt_pk_bf16_f32 v197, v116, v104
	v_cvt_pk_bf16_f32 v198, v118, v106
	v_cvt_pk_bf16_f32 v199, v120, v108
	s_waitcnt lgkmcnt(1)
	v_mfma_f32_32x32x16_bf16 v[32:47], v[244:247], v[188:191], v[32:47]
	v_cvt_pk_bf16_f32 v192, v221, v15
	v_cvt_pk_bf16_f32 v193, v13, v11
	v_cvt_pk_bf16_f32 v194, v99, v97
	v_cvt_pk_bf16_f32 v195, v113, v101
	s_waitcnt lgkmcnt(0)
	v_mfma_f32_32x32x16_bf16 v[16:31], v[248:251], v[188:191], v[16:31]
	v_cvt_pk_bf16_f32 v188, v115, v103
	v_cvt_pk_bf16_f32 v189, v117, v105
	v_cvt_pk_bf16_f32 v190, v119, v107
	v_cvt_pk_bf16_f32 v191, v121, v109
	v_cmp_gt_f32_e32 vcc, 1.0, v0
	s_cbranch_vccz .LBB0_1182
	v_pk_mul_f32 v[78:79], v[0:1], v[78:79] op_sel_hi:[0,1]
	v_pk_mul_f32 v[76:77], v[0:1], v[76:77] op_sel_hi:[0,1]
	v_pk_mul_f32 v[74:75], v[0:1], v[74:75] op_sel_hi:[0,1]
	v_pk_mul_f32 v[72:73], v[0:1], v[72:73] op_sel_hi:[0,1]
	v_pk_mul_f32 v[70:71], v[0:1], v[70:71] op_sel_hi:[0,1]
	v_pk_mul_f32 v[68:69], v[0:1], v[68:69] op_sel_hi:[0,1]
	v_pk_mul_f32 v[66:67], v[0:1], v[66:67] op_sel_hi:[0,1]
	v_pk_mul_f32 v[64:65], v[0:1], v[64:65] op_sel_hi:[0,1]
	v_pk_mul_f32 v[62:63], v[0:1], v[62:63] op_sel_hi:[0,1]
	v_pk_mul_f32 v[60:61], v[0:1], v[60:61] op_sel_hi:[0,1]
	v_pk_mul_f32 v[58:59], v[0:1], v[58:59] op_sel_hi:[0,1]
	v_pk_mul_f32 v[56:57], v[0:1], v[56:57] op_sel_hi:[0,1]
	v_pk_mul_f32 v[54:55], v[0:1], v[54:55] op_sel_hi:[0,1]
	v_pk_mul_f32 v[52:53], v[0:1], v[52:53] op_sel_hi:[0,1]
	v_pk_mul_f32 v[50:51], v[0:1], v[50:51] op_sel_hi:[0,1]
	v_pk_mul_f32 v[48:49], v[0:1], v[48:49] op_sel_hi:[0,1]
	v_pk_mul_f32 v[46:47], v[0:1], v[46:47] op_sel_hi:[0,1]
	v_pk_mul_f32 v[44:45], v[0:1], v[44:45] op_sel_hi:[0,1]
	v_pk_mul_f32 v[42:43], v[0:1], v[42:43] op_sel_hi:[0,1]
	v_pk_mul_f32 v[40:41], v[0:1], v[40:41] op_sel_hi:[0,1]
	v_pk_mul_f32 v[38:39], v[0:1], v[38:39] op_sel_hi:[0,1]
	v_pk_mul_f32 v[36:37], v[0:1], v[36:37] op_sel_hi:[0,1]
	v_pk_mul_f32 v[34:35], v[0:1], v[34:35] op_sel_hi:[0,1]
	v_pk_mul_f32 v[32:33], v[0:1], v[32:33] op_sel_hi:[0,1]
	v_pk_mul_f32 v[30:31], v[0:1], v[30:31] op_sel_hi:[0,1]
	v_pk_mul_f32 v[28:29], v[0:1], v[28:29] op_sel_hi:[0,1]
	v_pk_mul_f32 v[26:27], v[0:1], v[26:27] op_sel_hi:[0,1]
	v_pk_mul_f32 v[24:25], v[0:1], v[24:25] op_sel_hi:[0,1]
	v_pk_mul_f32 v[22:23], v[0:1], v[22:23] op_sel_hi:[0,1]
	v_pk_mul_f32 v[20:21], v[0:1], v[20:21] op_sel_hi:[0,1]
	v_pk_mul_f32 v[18:19], v[0:1], v[18:19] op_sel_hi:[0,1]
	v_pk_mul_f32 v[16:17], v[0:1], v[16:17] op_sel_hi:[0,1]

.LBB0_1189:
	v_add_u32_e32 v0, s57, v215
	ds_read_b128 v[2:5], v0
	ds_read_b128 v[6:9], v0 offset:32
	v_mov_b64_e32 v[110:111], v[94:95]
	v_mov_b64_e32 v[108:109], v[92:93]
	v_mov_b64_e32 v[106:107], v[90:91]
	s_waitcnt lgkmcnt(1)
	v_mfma_f32_32x32x16_bf16 v[112:127], v[2:5], v[128:131], v[80:95]
	ds_read_b128 v[2:5], v0 offset:12800
	ds_read_b128 v[10:13], v0 offset:12832
	v_mov_b64_e32 v[104:105], v[88:89]
	v_mov_b64_e32 v[102:103], v[86:87]
	v_mov_b64_e32 v[100:101], v[84:85]
	v_mov_b64_e32 v[98:99], v[82:83]
	v_mov_b64_e32 v[96:97], v[80:81]
	s_waitcnt lgkmcnt(2)
	v_mfma_f32_32x32x16_bf16 v[112:127], v[6:9], v[132:135], v[112:127]
	s_add_i32 s6, s36, 0xffffffa0
	s_lshl_b64 s[64:65], s[6:7], 1
	s_waitcnt lgkmcnt(1)
	v_mfma_f32_32x32x16_bf16 v[96:111], v[2:5], v[128:131], v[96:111]
	ds_read_b128 v[2:5], v0 offset:64
	ds_read_b128 v[6:9], v0 offset:96
	s_waitcnt lgkmcnt(2)
	v_mfma_f32_32x32x16_bf16 v[96:111], v[10:13], v[132:135], v[96:111]
	s_waitcnt lgkmcnt(1)
	v_mfma_f32_32x32x16_bf16 v[112:127], v[2:5], v[136:139], v[112:127]
	ds_read_b128 v[2:5], v0 offset:12864
	ds_read_b128 v[10:13], v0 offset:12896
	s_waitcnt lgkmcnt(1)
	v_mfma_f32_32x32x16_bf16 v[96:111], v[2:5], v[136:139], v[96:111]
	v_mfma_f32_32x32x16_bf16 v[112:127], v[6:9], v[140:143], v[112:127]
	ds_read_b128 v[2:5], v0 offset:128
	ds_read_b128 v[6:9], v0 offset:160
	s_waitcnt lgkmcnt(2)
	v_mfma_f32_32x32x16_bf16 v[96:111], v[10:13], v[140:143], v[96:111]
	s_waitcnt lgkmcnt(1)
	v_mfma_f32_32x32x16_bf16 v[112:127], v[2:5], v[144:147], v[112:127]
	ds_read_b128 v[2:5], v0 offset:12928
	ds_read_b128 v[10:13], v0 offset:12960
	s_waitcnt lgkmcnt(1)
	v_mfma_f32_32x32x16_bf16 v[96:111], v[2:5], v[144:147], v[96:111]
	v_mfma_f32_32x32x16_bf16 v[112:127], v[6:9], v[148:151], v[112:127]
	ds_read_b128 v[2:5], v0 offset:192
	ds_read_b128 v[6:9], v0 offset:224
	s_waitcnt lgkmcnt(2)
	v_mfma_f32_32x32x16_bf16 v[96:111], v[10:13], v[148:151], v[96:111]
	s_waitcnt lgkmcnt(1)
	v_mfma_f32_32x32x16_bf16 v[112:127], v[2:5], v[152:155], v[112:127]
	ds_read_b128 v[2:5], v0 offset:12992
	ds_read_b128 v[10:13], v0 offset:13024
	s_waitcnt lgkmcnt(1)
	v_mfma_f32_32x32x16_bf16 v[96:111], v[2:5], v[152:155], v[96:111]
	v_mfma_f32_32x32x16_bf16 v[112:127], v[6:9], v[156:159], v[112:127]
	ds_read_b128 v[2:5], v0 offset:256
	ds_read_b128 v[6:9], v0 offset:288
	s_waitcnt lgkmcnt(2)
	v_mfma_f32_32x32x16_bf16 v[96:111], v[10:13], v[156:159], v[96:111]
	s_waitcnt lgkmcnt(1)
	v_mfma_f32_32x32x16_bf16 v[112:127], v[2:5], v[160:163], v[112:127]
	ds_read_b128 v[2:5], v0 offset:13056
	ds_read_b128 v[10:13], v0 offset:13088
	s_waitcnt lgkmcnt(1)
	v_mfma_f32_32x32x16_bf16 v[96:111], v[2:5], v[160:163], v[96:111]
	v_mfma_f32_32x32x16_bf16 v[112:127], v[6:9], v[164:167], v[112:127]
	ds_read_b128 v[2:5], v0 offset:320
	ds_read_b128 v[6:9], v0 offset:352
	s_waitcnt lgkmcnt(2)
	v_mfma_f32_32x32x16_bf16 v[96:111], v[10:13], v[164:167], v[96:111]
	s_waitcnt lgkmcnt(1)
	v_mfma_f32_32x32x16_bf16 v[112:127], v[2:5], v[168:171], v[112:127]
	ds_read_b128 v[2:5], v0 offset:13120
	ds_read_b128 v[10:13], v0 offset:13152
	s_waitcnt lgkmcnt(1)
	v_mfma_f32_32x32x16_bf16 v[96:111], v[2:5], v[168:171], v[96:111]
	v_lshl_add_u64 v[2:3], v[206:207], 0, s[64:65]
	v_lshl_add_u64 v[4:5], v[218:219], 0, s[64:65]
	v_mfma_f32_32x32x16_bf16 v[112:127], v[6:9], v[172:175], v[112:127]
	global_load_dwordx4 v[6:9], v[2:3], off
	s_nop 0
	global_load_dwordx4 v[2:5], v[4:5], off
	s_waitcnt lgkmcnt(0)
	v_mfma_f32_32x32x16_bf16 v[96:111], v[10:13], v[172:175], v[96:111]
	s_add_i32 s6, s62, 0
	s_add_i32 s6, s6, 0x12c00
	v_add_u32_e32 v0, s6, v227
	v_add_u32_e32 v220, v0, v226
	ds_read2_b64 v[10:13], v220 offset1:2
	v_add_u32_e32 v0, s36, v225
	v_add_u32_e32 v14, 0xffffffa0, v0
	v_subrev_u32_e32 v15, 64, v0
	v_cmp_le_i32_e32 vcc, v14, v216
	v_add_u32_e32 v221, 0x1000, v220
	ds_read2_b64 v[236:239], v221 offset0:32 offset1:34
	v_cndmask_b32_e32 v229, v224, v112, vcc
	v_cmp_le_i32_e32 vcc, v15, v216
	s_waitcnt lgkmcnt(1)
	v_mfma_f32_32x32x16_bf16 v[64:79], v[10:13], v[200:203], v[64:79]
	v_subrev_u32_e32 v11, 63, v0
	v_cndmask_b32_e32 v231, v224, v96, vcc
	v_cmp_lt_i32_e32 vcc, v14, v216
	v_add_u32_e32 v12, 0xffffffa2, v0
	v_max_f32_e32 v10, v229, v229
	v_cndmask_b32_e32 v233, v229, v112, vcc
	v_cndmask_b32_e32 v232, v224, v113, vcc
	v_cmp_le_i32_e32 vcc, v11, v216
	v_max_f32_e32 v10, 0xff800000, v10
	s_nop 0
	v_cndmask_b32_e32 v234, v224, v97, vcc
	v_cmp_le_i32_e32 vcc, v12, v216
	v_subrev_u32_e32 v12, 62, v0
	v_max3_f32 v11, v231, s52, v234
	v_cndmask_b32_e32 v14, v224, v114, vcc
	v_cmp_le_i32_e32 vcc, v12, v216
	s_nop 1
	v_cndmask_b32_e32 v96, v224, v98, vcc
	v_max3_f32 v98, v10, v232, v14
	v_add_u32_e32 v10, 0xffffffa3, v0
	v_cmp_le_i32_e32 vcc, v10, v216
	v_subrev_u32_e32 v10, 61, v0
	s_nop 0
	v_cndmask_b32_e32 v15, v224, v115, vcc
	v_cmp_le_i32_e32 vcc, v10, v216
	s_nop 1
	v_cndmask_b32_e32 v97, v224, v99, vcc
	v_max3_f32 v99, v11, v96, v97
	v_add_u32_e32 v112, 0xffffffa8, v0
	v_cmp_le_i32_e32 vcc, v112, v216
	v_subrev_u32_e32 v113, 56, v0
	s_waitcnt lgkmcnt(0)
	v_mfma_f32_32x32x16_bf16 v[48:63], v[236:239], v[200:203], v[48:63]
	v_cndmask_b32_e32 v112, v224, v116, vcc
	v_cmp_le_i32_e32 vcc, v113, v216
	v_max3_f32 v116, v98, v15, v112
	v_add_u32_e32 v98, 0xffffffa9, v0
	v_cndmask_b32_e32 v114, v224, v100, vcc
	v_cmp_le_i32_e32 vcc, v98, v216
	v_subrev_u32_e32 v98, 55, v0
	v_add_u32_e32 v229, 0x2000, v220
	v_cndmask_b32_e32 v113, v224, v117, vcc
	v_cmp_le_i32_e32 vcc, v98, v216
	v_add_u32_e32 v98, 0xffffffaa, v0
	ds_read2_b64 v[10:13], v229 offset0:64 offset1:66
	v_cndmask_b32_e32 v115, v224, v101, vcc
	v_max3_f32 v117, v99, v114, v115
	v_cmp_le_i32_e32 vcc, v98, v216
	v_subrev_u32_e32 v99, 54, v0
	v_subrev_u32_e32 v101, 53, v0
	v_cndmask_b32_e32 v98, v224, v118, vcc
	v_cmp_le_i32_e32 vcc, v99, v216
	v_add_u32_e32 v99, 0xffffffab, v0
	s_nop 0
	v_cndmask_b32_e32 v100, v224, v102, vcc
	v_cmp_le_i32_e32 vcc, v99, v216
	v_max3_f32 v102, v116, v113, v98
	s_nop 0
	v_cndmask_b32_e32 v99, v224, v119, vcc
	v_cmp_le_i32_e32 vcc, v101, v216
	s_nop 1
	v_cndmask_b32_e32 v101, v224, v103, vcc
	v_max3_f32 v103, v117, v100, v101
	v_add_u32_e32 v116, 0xffffffb0, v0
	v_cmp_le_i32_e32 vcc, v116, v216
	v_subrev_u32_e32 v117, 48, v0
	s_waitcnt lgkmcnt(0)
	v_mfma_f32_32x32x16_bf16 v[32:47], v[10:13], v[200:203], v[32:47]
	v_cndmask_b32_e32 v116, v224, v120, vcc
	v_cmp_le_i32_e32 vcc, v117, v216
	v_add_u32_e32 v11, 0xffffffb1, v0
	v_add_u32_e32 v12, 0xffffffb2, v0
	v_cndmask_b32_e32 v118, v224, v104, vcc
	v_cmp_le_i32_e32 vcc, v11, v216
	v_subrev_u32_e32 v11, 47, v0
	v_add_u32_e32 v230, 0x3000, v220
	v_cndmask_b32_e32 v117, v224, v121, vcc
	v_cmp_le_i32_e32 vcc, v11, v216
	v_max3_f32 v10, v102, v99, v116
	ds_read2_b64 v[236:239], v230 offset0:96 offset1:98
	v_cndmask_b32_e32 v119, v224, v105, vcc
	v_cmp_le_i32_e32 vcc, v12, v216
	v_subrev_u32_e32 v12, 46, v0
	v_max3_f32 v11, v103, v118, v119
	v_cndmask_b32_e32 v102, v224, v122, vcc
	v_cmp_le_i32_e32 vcc, v12, v216
	v_add_u32_e32 v12, 0xffffffb3, v0
	v_max3_f32 v10, v10, v117, v102
	v_cndmask_b32_e32 v104, v224, v106, vcc
	v_cmp_le_i32_e32 vcc, v12, v216
	v_subrev_u32_e32 v12, 45, v0
	s_nop 0
	v_cndmask_b32_e32 v103, v224, v123, vcc
	v_cmp_le_i32_e32 vcc, v12, v216
	s_nop 1
	v_cndmask_b32_e32 v105, v224, v107, vcc
	v_max3_f32 v11, v11, v104, v105
	v_add_u32_e32 v12, 0xffffffb8, v0
	v_cmp_le_i32_e32 vcc, v12, v216
	v_subrev_u32_e32 v12, 40, v0
	s_waitcnt lgkmcnt(0)
	v_mfma_f32_32x32x16_bf16 v[16:31], v[236:239], v[200:203], v[16:31]
	v_cndmask_b32_e32 v106, v224, v124, vcc
	v_cmp_le_i32_e32 vcc, v12, v216
	v_add_u32_e32 v12, 0xffffffb9, v0
	v_max3_f32 v10, v10, v103, v106
	v_cndmask_b32_e32 v108, v224, v108, vcc
	v_cmp_le_i32_e32 vcc, v12, v216
	v_subrev_u32_e32 v12, 39, v0
	ds_read2_b64 v[120:123], v220 offset0:4 offset1:6
	v_cndmask_b32_e32 v107, v224, v125, vcc
	v_cmp_le_i32_e32 vcc, v12, v216
	v_add_u32_e32 v12, 0xffffffba, v0
	s_nop 0
	v_cndmask_b32_e32 v109, v224, v109, vcc
	v_cmp_le_i32_e32 vcc, v12, v216
	v_subrev_u32_e32 v12, 38, v0
	v_max3_f32 v11, v11, v108, v109
	v_cndmask_b32_e32 v124, v224, v126, vcc
	v_cmp_le_i32_e32 vcc, v12, v216
	v_max3_f32 v126, v10, v107, v124
	v_add_u32_e32 v10, 0xffffffbb, v0
	v_cndmask_b32_e32 v125, v224, v110, vcc
	v_cmp_le_i32_e32 vcc, v10, v216
	v_subrev_u32_e32 v0, 37, v0
	s_nop 0
	v_cndmask_b32_e32 v110, v224, v127, vcc
	v_cmp_le_i32_e32 vcc, v0, v216
	s_nop 1
	v_cndmask_b32_e32 v111, v224, v111, vcc
	v_max3_f32 v0, v11, v125, v111
	v_max3_f32 v0, v126, v110, v0
	v_mov_b32_e32 v126, v0
	ds_read2_b64 v[10:13], v221 offset0:36 offset1:38
	s_waitcnt lgkmcnt(1)
	v_mfma_f32_32x32x16_bf16 v[64:79], v[120:123], v[196:199], v[64:79]
	v_permlane32_swap_b32_e32 v126, v0
	v_max_f32_e32 v120, v126, v126
	v_max_f32_e32 v0, v0, v120
	v_cmp_lt_f32_e32 vcc, s53, v0
	s_cbranch_vccz .LBB0_1191
	v_max_f32_e32 v0, v0, v0
	v_max_f32_e32 v0, 0, v0
	v_add_f32_e32 v217, v217, v0
	v_sub_f32_e32 v233, v233, v0
	v_sub_f32_e32 v232, v232, v0
	v_sub_f32_e32 v231, v231, v0
	v_sub_f32_e32 v234, v234, v0
	v_pk_add_f32 v[14:15], v[14:15], v[0:1] op_sel_hi:[1,0] neg_lo:[0,1] neg_hi:[0,1]
	v_pk_add_f32 v[96:97], v[96:97], v[0:1] op_sel_hi:[1,0] neg_lo:[0,1] neg_hi:[0,1]
	v_pk_add_f32 v[112:113], v[112:113], v[0:1] op_sel_hi:[1,0] neg_lo:[0,1] neg_hi:[0,1]
	v_pk_add_f32 v[114:115], v[114:115], v[0:1] op_sel_hi:[1,0] neg_lo:[0,1] neg_hi:[0,1]
	v_pk_add_f32 v[98:99], v[98:99], v[0:1] op_sel_hi:[1,0] neg_lo:[0,1] neg_hi:[0,1]
	v_pk_add_f32 v[100:101], v[100:101], v[0:1] op_sel_hi:[1,0] neg_lo:[0,1] neg_hi:[0,1]
	v_pk_add_f32 v[116:117], v[116:117], v[0:1] op_sel_hi:[1,0] neg_lo:[0,1] neg_hi:[0,1]
	v_pk_add_f32 v[118:119], v[118:119], v[0:1] op_sel_hi:[1,0] neg_lo:[0,1] neg_hi:[0,1]
	v_pk_add_f32 v[102:103], v[102:103], v[0:1] op_sel_hi:[1,0] neg_lo:[0,1] neg_hi:[0,1]
	v_pk_add_f32 v[104:105], v[104:105], v[0:1] op_sel_hi:[1,0] neg_lo:[0,1] neg_hi:[0,1]
	v_pk_add_f32 v[106:107], v[106:107], v[0:1] op_sel_hi:[1,0] neg_lo:[0,1] neg_hi:[0,1]
	v_pk_add_f32 v[108:109], v[108:109], v[0:1] op_sel_hi:[1,0] neg_lo:[0,1] neg_hi:[0,1]
	v_sub_f32_e32 v124, v124, v0
	v_sub_f32_e32 v125, v125, v0
	v_pk_add_f32 v[110:111], v[110:111], v[0:1] op_sel_hi:[1,0] neg_lo:[0,1] neg_hi:[0,1]
	v_exp_f32_e64 v0, -v0
	v_xor_b32_e32 v80, 0x80000000, v217
	v_mov_b32_e32 v81, v80
	v_mov_b32_e32 v82, v80
	v_mov_b32_e32 v83, v80
	v_mov_b32_e32 v84, v80
	v_mov_b32_e32 v85, v80
	v_mov_b32_e32 v86, v80
	v_mov_b32_e32 v87, v80
	v_mov_b32_e32 v88, v80
	v_mov_b32_e32 v89, v80
	v_mov_b32_e32 v90, v80
	v_mov_b32_e32 v91, v80
	v_mov_b32_e32 v92, v80
	v_mov_b32_e32 v93, v80
	v_mov_b32_e32 v94, v80
	v_mov_b32_e32 v95, v80
	s_branch .LBB0_1192

.LBB0_1192:
	s_waitcnt lgkmcnt(0)
	v_mfma_f32_32x32x16_bf16 v[48:63], v[10:13], v[196:199], v[48:63]
	ds_read2_b64 v[200:203], v229 offset0:68 offset1:70
	v_exp_f32_e32 v122, v233
	v_exp_f32_e32 v123, v231
	v_exp_f32_e32 v120, v232
	v_exp_f32_e32 v121, v234
	s_waitcnt lgkmcnt(0)
	v_mfma_f32_32x32x16_bf16 v[32:47], v[200:203], v[196:199], v[32:47]
	ds_read2_b64 v[232:235], v230 offset0:100 offset1:102
	v_exp_f32_e32 v12, v14
	v_exp_f32_e32 v13, v96
	v_exp_f32_e32 v10, v15
	v_exp_f32_e32 v11, v97
	s_waitcnt lgkmcnt(0)
	v_mfma_f32_32x32x16_bf16 v[16:31], v[232:235], v[196:199], v[16:31]
	ds_read2_b64 v[200:203], v220 offset0:8 offset1:10
	v_exp_f32_e32 v96, v112
	v_exp_f32_e32 v97, v114
	v_exp_f32_e32 v14, v113
	v_exp_f32_e32 v15, v115
	s_waitcnt lgkmcnt(0)
	v_mfma_f32_32x32x16_bf16 v[64:79], v[200:203], v[192:195], v[64:79]
	ds_read2_b64 v[196:199], v221 offset0:40 offset1:42
	v_exp_f32_e32 v112, v98
	v_exp_f32_e32 v113, v100
	v_exp_f32_e32 v98, v99
	v_exp_f32_e32 v99, v101
	s_waitcnt lgkmcnt(0)
	v_mfma_f32_32x32x16_bf16 v[48:63], v[196:199], v[192:195], v[48:63]
	ds_read2_b64 v[200:203], v229 offset0:72 offset1:74
	v_exp_f32_e32 v114, v116
	v_exp_f32_e32 v115, v118
	v_exp_f32_e32 v100, v117
	v_exp_f32_e32 v101, v119
	s_waitcnt lgkmcnt(0)
	v_mfma_f32_32x32x16_bf16 v[32:47], v[200:203], v[192:195], v[32:47]
	ds_read2_b64 v[196:199], v230 offset0:104 offset1:106
	v_exp_f32_e32 v116, v102
	v_exp_f32_e32 v117, v104
	v_exp_f32_e32 v102, v103
	v_exp_f32_e32 v103, v105
	s_waitcnt lgkmcnt(0)
	v_mfma_f32_32x32x16_bf16 v[16:31], v[196:199], v[192:195], v[16:31]
	ds_read2_b64 v[200:203], v220 offset0:12 offset1:14
	v_exp_f32_e32 v118, v106
	v_exp_f32_e32 v119, v108
	v_exp_f32_e32 v104, v107
	v_exp_f32_e32 v105, v109
	s_waitcnt lgkmcnt(0)
	v_mfma_f32_32x32x16_bf16 v[64:79], v[200:203], v[188:191], v[64:79]
	ds_read2_b64 v[192:195], v221 offset0:44 offset1:46
	v_exp_f32_e32 v108, v124
	v_exp_f32_e32 v109, v125
	v_exp_f32_e32 v106, v110
	v_exp_f32_e32 v107, v111
	s_waitcnt lgkmcnt(0)
	v_mfma_f32_32x32x16_bf16 v[48:63], v[192:195], v[188:191], v[48:63]
	ds_read2_b64 v[124:127], v229 offset0:76 offset1:78
	v_cvt_pk_bf16_f32 v200, v122, v120
	v_cvt_pk_bf16_f32 v201, v12, v10
	v_cvt_pk_bf16_f32 v202, v96, v14
	v_cvt_pk_bf16_f32 v203, v112, v98
	v_cvt_pk_bf16_f32 v196, v114, v100
	v_cvt_pk_bf16_f32 v197, v116, v102
	v_cvt_pk_bf16_f32 v198, v118, v104
	v_cvt_pk_bf16_f32 v199, v108, v106
	s_waitcnt lgkmcnt(0)
	v_mfma_f32_32x32x16_bf16 v[32:47], v[124:127], v[188:191], v[32:47]
	ds_read2_b64 v[230:233], v230 offset0:108 offset1:110
	v_cvt_pk_bf16_f32 v192, v123, v121
	v_cvt_pk_bf16_f32 v193, v13, v11
	v_cvt_pk_bf16_f32 v194, v97, v15
	v_cvt_pk_bf16_f32 v195, v113, v99
	s_waitcnt lgkmcnt(0)
	v_mfma_f32_32x32x16_bf16 v[16:31], v[230:233], v[188:191], v[16:31]
	v_cvt_pk_bf16_f32 v188, v115, v101
	v_cvt_pk_bf16_f32 v189, v117, v103
	v_cvt_pk_bf16_f32 v190, v119, v105
	v_cvt_pk_bf16_f32 v191, v109, v107
	v_cmp_gt_f32_e32 vcc, 1.0, v0
	s_cbranch_vccz .LBB0_1194
	v_pk_mul_f32 v[78:79], v[0:1], v[78:79] op_sel_hi:[0,1]
	v_pk_mul_f32 v[76:77], v[0:1], v[76:77] op_sel_hi:[0,1]
	v_pk_mul_f32 v[74:75], v[0:1], v[74:75] op_sel_hi:[0,1]
	v_pk_mul_f32 v[72:73], v[0:1], v[72:73] op_sel_hi:[0,1]
	v_pk_mul_f32 v[70:71], v[0:1], v[70:71] op_sel_hi:[0,1]
	v_pk_mul_f32 v[68:69], v[0:1], v[68:69] op_sel_hi:[0,1]
	v_pk_mul_f32 v[66:67], v[0:1], v[66:67] op_sel_hi:[0,1]
	v_pk_mul_f32 v[64:65], v[0:1], v[64:65] op_sel_hi:[0,1]
	v_pk_mul_f32 v[62:63], v[0:1], v[62:63] op_sel_hi:[0,1]
	v_pk_mul_f32 v[60:61], v[0:1], v[60:61] op_sel_hi:[0,1]
	v_pk_mul_f32 v[58:59], v[0:1], v[58:59] op_sel_hi:[0,1]
	v_pk_mul_f32 v[56:57], v[0:1], v[56:57] op_sel_hi:[0,1]
	v_pk_mul_f32 v[54:55], v[0:1], v[54:55] op_sel_hi:[0,1]
	v_pk_mul_f32 v[52:53], v[0:1], v[52:53] op_sel_hi:[0,1]
	v_pk_mul_f32 v[50:51], v[0:1], v[50:51] op_sel_hi:[0,1]
	v_pk_mul_f32 v[48:49], v[0:1], v[48:49] op_sel_hi:[0,1]
	v_pk_mul_f32 v[46:47], v[0:1], v[46:47] op_sel_hi:[0,1]
	v_pk_mul_f32 v[44:45], v[0:1], v[44:45] op_sel_hi:[0,1]
	v_pk_mul_f32 v[42:43], v[0:1], v[42:43] op_sel_hi:[0,1]
	v_pk_mul_f32 v[40:41], v[0:1], v[40:41] op_sel_hi:[0,1]
	v_pk_mul_f32 v[38:39], v[0:1], v[38:39] op_sel_hi:[0,1]
	v_pk_mul_f32 v[36:37], v[0:1], v[36:37] op_sel_hi:[0,1]
	v_pk_mul_f32 v[34:35], v[0:1], v[34:35] op_sel_hi:[0,1]
	v_pk_mul_f32 v[32:33], v[0:1], v[32:33] op_sel_hi:[0,1]
	v_pk_mul_f32 v[30:31], v[0:1], v[30:31] op_sel_hi:[0,1]
	v_pk_mul_f32 v[28:29], v[0:1], v[28:29] op_sel_hi:[0,1]
	v_pk_mul_f32 v[26:27], v[0:1], v[26:27] op_sel_hi:[0,1]
	v_pk_mul_f32 v[24:25], v[0:1], v[24:25] op_sel_hi:[0,1]
	v_pk_mul_f32 v[22:23], v[0:1], v[22:23] op_sel_hi:[0,1]
	v_pk_mul_f32 v[20:21], v[0:1], v[20:21] op_sel_hi:[0,1]
	v_pk_mul_f32 v[18:19], v[0:1], v[18:19] op_sel_hi:[0,1]
	v_pk_mul_f32 v[16:17], v[0:1], v[16:17] op_sel_hi:[0,1]
